# e20: sample-attention loader waves: rolling per-pair pipeline (counted vmcnt(30), reload right after each pair's LDS write), flat->global
# baseline (speedup 1.0000x reference)
; __device__ __forceinline__ void attn_sample_unit(int b, int h, int split, const bf16* __restrict__ Q, const float* __restrict__ cache_k, const float* __restrict__ cache_v, ...
;     ...
;     SL_LOAD(0); SL_WRITE(0); SL_LOAD(1);
.LBB0_368:
	s_and_b64 vcc, exec, s[18:19]
	s_cbranch_vccz .LBB0_354
	v_readfirstlane_b32 s5, v101
	s_ashr_i32 s20, s48, 4
	s_lshl_b32 s38, s5, 24
	s_lshl_b32 s5, s5, 19
	s_ashr_i32 s21, s20, 31
	s_or_b32 s42, s5, 0xf00000
	s_lshl_b64 s[6:7], s[20:21], 12
	s_lshl_b32 s5, s64, 11
	s_add_i32 s10, s36, -4
	s_or_b32 s5, s6, s5
	s_add_u32 s6, s5, s10
	s_addc_u32 s7, s7, 0
	s_lshl_b64 s[18:19], s[6:7], 13
	s_add_u32 s5, s44, s18
	s_addc_u32 s6, s45, s19
	s_lshl_b32 s40, s4, 2
	s_add_u32 s4, s5, s40
	s_addc_u32 s5, s6, 0
	s_add_u32 s6, s46, s18
	s_addc_u32 s7, s47, s19
	s_add_u32 s6, s6, s40
	s_addc_u32 s7, s7, 0
	global_load_dwordx4 v[108:111], v100, s[4:5] nt
	global_load_dwordx4 v[112:115], v100, s[6:7] nt
	v_mov_b32_e32 v101, v3
	v_lshl_add_u64 v[4:5], s[4:5], 0, v[100:101]
	v_lshl_add_u64 v[6:7], s[6:7], 0, v[100:101]
	v_lshl_add_u64 v[4:5], v[4:5], 0, s[72:73]
	v_lshl_add_u64 v[6:7], v[6:7], 0, s[72:73]
	global_load_dwordx4 v[116:119], v[4:5], off nt
	global_load_dwordx4 v[120:123], v[6:7], off nt
	v_lshl_add_u64 v[4:5], v[4:5], 0, s[72:73]
	v_lshl_add_u64 v[6:7], v[6:7], 0, s[72:73]
	global_load_dwordx4 v[124:127], v[4:5], off nt
	global_load_dwordx4 v[128:131], v[6:7], off nt
	v_lshl_add_u64 v[4:5], v[4:5], 0, s[72:73]
	v_lshl_add_u64 v[6:7], v[6:7], 0, s[72:73]
	global_load_dwordx4 v[148:151], v[4:5], off nt
	global_load_dwordx4 v[152:155], v[6:7], off nt
	v_lshl_add_u64 v[4:5], v[4:5], 0, s[72:73]
	v_lshl_add_u64 v[6:7], v[6:7], 0, s[72:73]
	global_load_dwordx4 v[172:175], v[4:5], off nt
	global_load_dwordx4 v[92:95], v[6:7], off nt
	v_lshl_add_u64 v[4:5], v[4:5], 0, s[72:73]
	v_lshl_add_u64 v[6:7], v[6:7], 0, s[72:73]
	global_load_dwordx4 v[88:91], v[4:5], off nt
	global_load_dwordx4 v[84:87], v[6:7], off nt
	v_lshl_add_u64 v[4:5], v[4:5], 0, s[72:73]
	v_lshl_add_u64 v[6:7], v[6:7], 0, s[72:73]
	global_load_dwordx4 v[80:83], v[4:5], off nt
	global_load_dwordx4 v[76:79], v[6:7], off nt
	v_lshl_add_u64 v[4:5], v[4:5], 0, s[72:73]
	v_lshl_add_u64 v[6:7], v[6:7], 0, s[72:73]
	global_load_dwordx4 v[72:75], v[4:5], off nt
	global_load_dwordx4 v[68:71], v[6:7], off nt
	v_lshl_add_u64 v[4:5], v[4:5], 0, s[72:73]
	v_lshl_add_u64 v[6:7], v[6:7], 0, s[72:73]
	global_load_dwordx4 v[64:67], v[4:5], off nt
	global_load_dwordx4 v[60:63], v[6:7], off nt
	v_lshl_add_u64 v[4:5], v[4:5], 0, s[72:73]
	v_lshl_add_u64 v[6:7], v[6:7], 0, s[72:73]
	global_load_dwordx4 v[56:59], v[4:5], off nt
	global_load_dwordx4 v[52:55], v[6:7], off nt
	v_lshl_add_u64 v[4:5], v[4:5], 0, s[72:73]
	v_lshl_add_u64 v[6:7], v[6:7], 0, s[72:73]
	global_load_dwordx4 v[48:51], v[4:5], off nt
	global_load_dwordx4 v[44:47], v[6:7], off nt
	v_lshl_add_u64 v[4:5], v[4:5], 0, s[72:73]
	v_lshl_add_u64 v[6:7], v[6:7], 0, s[72:73]
	global_load_dwordx4 v[40:43], v[4:5], off nt
	global_load_dwordx4 v[36:39], v[6:7], off nt
	v_lshl_add_u64 v[4:5], v[4:5], 0, s[72:73]
	v_lshl_add_u64 v[6:7], v[6:7], 0, s[72:73]
	global_load_dwordx4 v[32:35], v[4:5], off nt
	global_load_dwordx4 v[28:31], v[6:7], off nt
	v_lshl_add_u64 v[4:5], v[4:5], 0, s[72:73]
	v_lshl_add_u64 v[6:7], v[6:7], 0, s[72:73]
	global_load_dwordx4 v[24:27], v[4:5], off nt
	global_load_dwordx4 v[20:23], v[6:7], off nt
	v_lshl_add_u64 v[4:5], v[4:5], 0, s[72:73]
	v_lshl_add_u64 v[6:7], v[6:7], 0, s[72:73]
	global_load_dwordx4 v[16:19], v[4:5], off nt
	global_load_dwordx4 v[12:15], v[6:7], off nt
	v_lshl_add_u64 v[96:97], v[4:5], 0, s[72:73]
	v_lshl_add_u64 v[98:99], v[6:7], 0, s[72:73]
	global_load_dwordx4 v[8:11], v[96:97], off nt
	global_load_dwordx4 v[4:7], v[98:99], off nt
	v_lshl_add_u64 v[96:97], v[96:97], 0, s[72:73]
	v_lshl_add_u64 v[98:99], v[98:99], 0, s[72:73]
	v_lshlrev_b32_e32 v2, 3, v106
	v_lshlrev_b32_e32 v139, 14, v107
	v_and_b32_e32 v98, 0xf0, v2
	s_lshl_b32 s5, s10, 4
	s_lshl_b32 s6, s10, 1
	v_add_u32_e32 v97, 0, v139
	s_lshl_b32 s43, s10, 8
	v_bitop3_b32 v141, s5, v98, v202 bitop3:0x6c
	s_and_b32 s5, s10, 0xfffff0
	s_and_b32 s6, s6, 8
	v_and_b32_e32 v138, 8, v2
	v_add_u32_e32 v99, s43, v97
	s_or_b32 s5, s6, s5
	s_lshr_b32 s6, s10, 1
	v_lshlrev_b32_e32 v2, 9, v132
	v_bfe_u32 v96, v104, 3, 2
	s_bfe_u32 s4, s37, 0x20006
	v_add3_u32 v99, v99, v141, v138
	s_and_b32 s6, s6, 4
	s_lshr_b32 s5, s5, 1
	v_and_b32_e32 v140, 0x4000, v2
	s_waitcnt vmcnt(0)
	v_cvt_pk_bf16_f32 v102, v108, v109
	v_cvt_pk_bf16_f32 v103, v110, v111
	ds_write_b64 v99, v[102:103]
	v_or_b32_e32 v99, s5, v96
	s_or_b32 s5, s6, s4
	v_add_u32_e32 v2, 0, v140
	v_lshlrev_b32_e32 v142, 9, v99
	s_lshl_b32 s65, s5, 6
	v_and_b32_e32 v136, 48, v105
	v_and_b32_e32 v137, 8, v105
	v_add3_u32 v99, v2, v142, s65
	s_lshl_b32 s5, s36, 4
	s_lshl_b32 s6, s36, 1
	v_add3_u32 v99, v99, v136, v137
	s_lshl_b32 s66, s36, 8
	v_bitop3_b32 v143, s5, v98, v202 bitop3:0x6c
	s_and_b32 s5, s36, 0xfffff0
	s_and_b32 s6, s6, 8
	v_cvt_pk_bf16_f32 v102, v112, v113
	v_cvt_pk_bf16_f32 v103, v114, v115
	ds_write_b64 v99, v[102:103] offset:32768
	v_add_u32_e32 v99, s66, v97
	s_or_b32 s5, s6, s5
	s_lshr_b32 s6, s36, 1
	v_add3_u32 v99, v99, v143, v138
	s_and_b32 s6, s6, 4
	s_lshr_b32 s5, s5, 1
	s_waitcnt lgkmcnt(0)
	v_cvt_pk_bf16_f32 v102, v116, v117
	v_cvt_pk_bf16_f32 v103, v118, v119
	ds_write_b64 v99, v[102:103]
	v_or_b32_e32 v99, s5, v96
	s_or_b32 s5, s6, s4
	v_lshlrev_b32_e32 v144, 9, v99
	s_lshl_b32 s41, s5, 6
	s_add_i32 s5, s36, 4
	v_add3_u32 v99, v2, v144, s41
	s_lshl_b32 s6, s5, 4
	s_lshl_b32 s7, s5, 1
	v_add3_u32 v99, v99, v136, v137
	s_lshl_b32 s67, s5, 8
	v_bitop3_b32 v145, s6, v98, v202 bitop3:0x6c
	s_and_b32 s6, s5, 0xfffff0
	s_and_b32 s7, s7, 8
	v_cvt_pk_bf16_f32 v102, v120, v121
	v_cvt_pk_bf16_f32 v103, v122, v123
	ds_write_b64 v99, v[102:103] offset:32768
	v_add_u32_e32 v99, s67, v97
	s_or_b32 s6, s7, s6
	s_lshr_b32 s5, s5, 1
	v_add3_u32 v99, v99, v145, v138
	s_and_b32 s5, s5, 4
	s_lshr_b32 s6, s6, 1
	v_cvt_pk_bf16_f32 v102, v124, v125
	v_cvt_pk_bf16_f32 v103, v126, v127
	ds_write_b64 v99, v[102:103]
	v_or_b32_e32 v99, s6, v96
	s_or_b32 s5, s5, s4
	v_lshlrev_b32_e32 v146, 9, v99
	s_lshl_b32 s77, s5, 6
	s_add_i32 s5, s36, 8
	v_add3_u32 v99, v2, v146, s77
	s_lshl_b32 s6, s5, 4
	s_lshl_b32 s7, s5, 1
	v_add3_u32 v99, v99, v136, v137
	s_lshl_b32 s78, s5, 8
	v_bitop3_b32 v147, s6, v98, v202 bitop3:0x6c
	s_and_b32 s6, s5, 0xfffff0
	s_and_b32 s7, s7, 8
	v_cvt_pk_bf16_f32 v102, v128, v129
	v_cvt_pk_bf16_f32 v103, v130, v131
	ds_write_b64 v99, v[102:103] offset:32768
	v_add_u32_e32 v99, s78, v97
	s_or_b32 s6, s7, s6
	s_lshr_b32 s5, s5, 1
	v_add3_u32 v99, v99, v147, v138
	s_and_b32 s5, s5, 4
	s_lshr_b32 s6, s6, 1
	v_cvt_pk_bf16_f32 v102, v148, v149
	v_cvt_pk_bf16_f32 v103, v150, v151
	ds_write_b64 v99, v[102:103]
	v_or_b32_e32 v99, s6, v96
	s_or_b32 s5, s5, s4
	v_lshlrev_b32_e32 v148, 9, v99
	s_lshl_b32 s79, s5, 6
	s_add_i32 s5, s36, 12
	v_add3_u32 v99, v2, v148, s79
	s_lshl_b32 s6, s5, 4
	s_lshl_b32 s7, s5, 1
	v_add3_u32 v99, v99, v136, v137
	s_lshl_b32 s80, s5, 8
	v_bitop3_b32 v149, s6, v98, v202 bitop3:0x6c
	s_and_b32 s6, s5, 0xfffff0
	s_and_b32 s7, s7, 8
	s_lshr_b32 s5, s5, 1
	v_cvt_pk_bf16_f32 v102, v152, v153
	v_cvt_pk_bf16_f32 v103, v154, v155
	ds_write_b64 v99, v[102:103] offset:32768
	v_add_u32_e32 v99, s80, v97
	s_or_b32 s6, s7, s6
	s_and_b32 s5, s5, 4
	v_add3_u32 v99, v99, v149, v138
	s_lshr_b32 s6, s6, 1
	s_or_b32 s5, s5, s4
	v_cvt_pk_bf16_f32 v102, v172, v173
	v_cvt_pk_bf16_f32 v103, v174, v175
	ds_write_b64 v99, v[102:103]
	v_cvt_pk_bf16_f32 v92, v92, v93
	v_cvt_pk_bf16_f32 v93, v94, v95
	v_or_b32_e32 v94, s6, v96
	s_lshl_b32 s81, s5, 6
	s_add_i32 s5, s36, 16
	v_lshlrev_b32_e32 v150, 9, v94
	s_lshl_b32 s6, s5, 4
	v_add3_u32 v94, v2, v150, s81
	s_lshl_b32 s82, s5, 8
	v_bitop3_b32 v151, s6, v98, v202 bitop3:0x6c
	s_and_b32 s6, s5, 0xfffff0
	s_lshl_b32 s5, s5, 1
	v_add3_u32 v94, v94, v136, v137
	s_and_b32 s5, s5, 8
	ds_write_b64 v94, v[92:93] offset:32768
	v_cvt_pk_bf16_f32 v88, v88, v89
	v_cvt_pk_bf16_f32 v89, v90, v91
	v_add_u32_e32 v90, s82, v97
	s_or_b32 s5, s5, s6
	v_add3_u32 v90, v90, v151, v138
	s_lshr_b32 s5, s5, 1
	ds_write_b64 v90, v[88:89]
	v_cvt_pk_bf16_f32 v84, v84, v85
	v_cvt_pk_bf16_f32 v85, v86, v87
	v_or_b32_e32 v86, s5, v96
	v_lshlrev_b32_e32 v152, 9, v86
	s_add_i32 s5, s36, 20
	v_add3_u32 v86, v2, v152, s41
	s_lshl_b32 s6, s5, 4
	s_lshl_b32 s7, s5, 1
	v_add3_u32 v86, v86, v136, v137
	s_lshl_b32 s83, s5, 8
	v_bitop3_b32 v153, s6, v98, v202 bitop3:0x6c
	s_and_b32 s6, s5, 0xfffff0
	s_and_b32 s7, s7, 8
	ds_write_b64 v86, v[84:85] offset:32768
	v_cvt_pk_bf16_f32 v80, v80, v81
	v_cvt_pk_bf16_f32 v81, v82, v83
	v_add_u32_e32 v82, s83, v97
	s_or_b32 s6, s7, s6
	s_lshr_b32 s5, s5, 1
	v_add3_u32 v82, v82, v153, v138
	s_and_b32 s5, s5, 4
	s_lshr_b32 s6, s6, 1
	ds_write_b64 v82, v[80:81]
	v_cvt_pk_bf16_f32 v76, v76, v77
	v_cvt_pk_bf16_f32 v77, v78, v79
	v_or_b32_e32 v78, s6, v96
	s_or_b32 s5, s5, s4
	v_lshlrev_b32_e32 v154, 9, v78
	s_lshl_b32 s84, s5, 6
	s_add_i32 s5, s36, 24
	v_add3_u32 v78, v2, v154, s84
	s_lshl_b32 s6, s5, 4
	s_lshl_b32 s7, s5, 1
	v_add3_u32 v78, v78, v136, v137
	s_lshl_b32 s85, s5, 8
	v_bitop3_b32 v155, s6, v98, v202 bitop3:0x6c
	s_and_b32 s6, s5, 0xfffff0
	s_and_b32 s7, s7, 8
	ds_write_b64 v78, v[76:77] offset:32768
	v_cvt_pk_bf16_f32 v72, v72, v73
	v_cvt_pk_bf16_f32 v73, v74, v75
	v_add_u32_e32 v74, s85, v97
	s_or_b32 s6, s7, s6
	s_lshr_b32 s5, s5, 1
	v_add3_u32 v74, v74, v155, v138
	s_and_b32 s5, s5, 4
	s_lshr_b32 s6, s6, 1
	ds_write_b64 v74, v[72:73]
	v_cvt_pk_bf16_f32 v68, v68, v69
	v_cvt_pk_bf16_f32 v69, v70, v71
	v_or_b32_e32 v70, s6, v96
	s_or_b32 s5, s5, s4
	v_lshlrev_b32_e32 v172, 9, v70
	s_lshl_b32 s86, s5, 6
	s_add_i32 s5, s36, 28
	v_add3_u32 v70, v2, v172, s86
	s_lshl_b32 s6, s5, 4
	s_lshl_b32 s7, s5, 1
	v_add3_u32 v70, v70, v136, v137
	s_lshl_b32 s87, s5, 8
	v_bitop3_b32 v173, s6, v98, v202 bitop3:0x6c
	s_and_b32 s6, s5, 0xfffff0
	s_and_b32 s7, s7, 8
	s_lshr_b32 s5, s5, 1
	ds_write_b64 v70, v[68:69] offset:32768
	v_cvt_pk_bf16_f32 v64, v64, v65
	v_cvt_pk_bf16_f32 v65, v66, v67
	v_add_u32_e32 v66, s87, v97
	s_or_b32 s6, s7, s6
	s_and_b32 s5, s5, 4
	v_add3_u32 v66, v66, v173, v138
	s_lshr_b32 s6, s6, 1
	s_or_b32 s5, s5, s4
	ds_write_b64 v66, v[64:65]
	v_cvt_pk_bf16_f32 v60, v60, v61
	v_cvt_pk_bf16_f32 v61, v62, v63
	v_or_b32_e32 v62, s6, v96
	s_lshl_b32 s88, s5, 6
	s_add_i32 s5, s36, 32
	v_lshlrev_b32_e32 v174, 9, v62
	s_lshl_b32 s6, s5, 4
	v_add3_u32 v62, v2, v174, s88
	s_lshl_b32 s89, s5, 8
	v_bitop3_b32 v175, s6, v98, v202 bitop3:0x6c
	s_and_b32 s6, s5, 0xfffff0
	s_lshl_b32 s5, s5, 1
	v_add3_u32 v62, v62, v136, v137
	s_and_b32 s5, s5, 8
	ds_write_b64 v62, v[60:61] offset:32768
	v_cvt_pk_bf16_f32 v56, v56, v57
	v_cvt_pk_bf16_f32 v57, v58, v59
	v_add_u32_e32 v58, s89, v97
	s_or_b32 s5, s5, s6
	v_add3_u32 v58, v58, v175, v138
	s_lshr_b32 s5, s5, 1
	ds_write_b64 v58, v[56:57]
	v_cvt_pk_bf16_f32 v52, v52, v53
	v_cvt_pk_bf16_f32 v53, v54, v55
	v_or_b32_e32 v54, s5, v96
	v_lshlrev_b32_e32 v176, 9, v54
	s_add_i32 s5, s36, 36
	v_add3_u32 v54, v2, v176, s41
	s_lshl_b32 s6, s5, 4
	s_lshl_b32 s7, s5, 1
	v_add3_u32 v54, v54, v136, v137
	s_lshl_b32 s90, s5, 8
	v_bitop3_b32 v177, s6, v98, v202 bitop3:0x6c
	s_and_b32 s6, s5, 0xfffff0
	s_and_b32 s7, s7, 8
	ds_write_b64 v54, v[52:53] offset:32768
	v_cvt_pk_bf16_f32 v48, v48, v49
	v_cvt_pk_bf16_f32 v49, v50, v51
	v_add_u32_e32 v50, s90, v97
	s_or_b32 s6, s7, s6
	s_lshr_b32 s5, s5, 1
	v_add3_u32 v50, v50, v177, v138
	s_and_b32 s5, s5, 4
	s_lshr_b32 s6, s6, 1
	ds_write_b64 v50, v[48:49]
	v_cvt_pk_bf16_f32 v44, v44, v45
	v_cvt_pk_bf16_f32 v45, v46, v47
	v_or_b32_e32 v46, s6, v96
	s_or_b32 s5, s5, s4
	v_lshlrev_b32_e32 v178, 9, v46
	s_lshl_b32 s91, s5, 6
	s_add_i32 s5, s36, 40
	v_add3_u32 v46, v2, v178, s91
	s_lshl_b32 s6, s5, 4
	s_lshl_b32 s7, s5, 1
	v_add3_u32 v46, v46, v136, v137
	s_lshl_b32 s92, s5, 8
	v_bitop3_b32 v179, s6, v98, v202 bitop3:0x6c
	s_and_b32 s6, s5, 0xfffff0
	s_and_b32 s7, s7, 8
	ds_write_b64 v46, v[44:45] offset:32768
	v_cvt_pk_bf16_f32 v40, v40, v41
	v_cvt_pk_bf16_f32 v41, v42, v43
	v_add_u32_e32 v42, s92, v97
	s_or_b32 s6, s7, s6
	s_lshr_b32 s5, s5, 1
	v_add3_u32 v42, v42, v179, v138
	s_and_b32 s5, s5, 4
	s_lshr_b32 s6, s6, 1
	ds_write_b64 v42, v[40:41]
	v_cvt_pk_bf16_f32 v36, v36, v37
	v_cvt_pk_bf16_f32 v37, v38, v39
	v_or_b32_e32 v38, s6, v96
	s_or_b32 s5, s5, s4
	s_mov_b32 s34, s93
	v_lshlrev_b32_e32 v180, 9, v38
	s_lshl_b32 s93, s5, 6
	s_add_i32 s5, s36, 44
	v_add3_u32 v38, v2, v180, s93
	s_lshl_b32 s6, s5, 4
	s_lshl_b32 s7, s5, 1
	s_mov_b64 s[26:27], s[94:95]
	v_add3_u32 v38, v38, v136, v137
	s_lshl_b32 s94, s5, 8
	v_bitop3_b32 v181, s6, v98, v202 bitop3:0x6c
	s_and_b32 s6, s5, 0xfffff0
	s_and_b32 s7, s7, 8
	s_lshr_b32 s5, s5, 1
	ds_write_b64 v38, v[36:37] offset:32768
	v_cvt_pk_bf16_f32 v32, v32, v33
	v_cvt_pk_bf16_f32 v33, v34, v35
	v_add_u32_e32 v34, s94, v97
	s_or_b32 s6, s7, s6
	s_and_b32 s5, s5, 4
	v_add3_u32 v34, v34, v181, v138
	s_lshr_b32 s6, s6, 1
	s_or_b32 s5, s5, s4
	ds_write_b64 v34, v[32:33]
	v_cvt_pk_bf16_f32 v28, v28, v29
	v_cvt_pk_bf16_f32 v29, v30, v31
	v_or_b32_e32 v30, s6, v96
	s_lshl_b32 s95, s5, 6
	s_add_i32 s5, s36, 48
	v_lshlrev_b32_e32 v182, 9, v30
	s_lshl_b32 s6, s5, 4
	s_mov_b32 s75, s96
	v_add3_u32 v30, v2, v182, s95
	s_lshl_b32 s96, s5, 8
	v_bitop3_b32 v183, s6, v98, v202 bitop3:0x6c
	s_and_b32 s6, s5, 0xfffff0
	s_lshl_b32 s5, s5, 1
	v_add3_u32 v30, v30, v136, v137
	s_and_b32 s5, s5, 8
	ds_write_b64 v30, v[28:29] offset:32768
	v_cvt_pk_bf16_f32 v24, v24, v25
	v_cvt_pk_bf16_f32 v25, v26, v27
	v_add_u32_e32 v26, s96, v97
	s_or_b32 s5, s5, s6
	v_add3_u32 v26, v26, v183, v138
	s_lshr_b32 s5, s5, 1
	ds_write_b64 v26, v[24:25]
	v_cvt_pk_bf16_f32 v20, v20, v21
	v_cvt_pk_bf16_f32 v21, v22, v23
	v_or_b32_e32 v22, s5, v96
	v_lshlrev_b32_e32 v184, 9, v22
	s_add_i32 s5, s36, 52
	v_add3_u32 v22, v2, v184, s41
	s_lshl_b32 s6, s5, 4
	s_lshl_b32 s7, s5, 1
	v_add3_u32 v22, v22, v136, v137
	s_lshl_b32 s97, s5, 8
	v_bitop3_b32 v185, s6, v98, v202 bitop3:0x6c
	s_and_b32 s6, s5, 0xfffff0
	s_and_b32 s7, s7, 8
	s_lshr_b32 s5, s5, 1
	ds_write_b64 v22, v[20:21] offset:32768
	v_cvt_pk_bf16_f32 v16, v16, v17
	v_cvt_pk_bf16_f32 v17, v18, v19
	v_add_u32_e32 v18, s97, v97
	s_or_b32 s6, s7, s6
	s_and_b32 s5, s5, 4
	v_add3_u32 v18, v18, v185, v138
	s_lshr_b32 s6, s6, 1
	s_or_b32 s5, s5, s4
	s_add_i32 s36, s36, 56
	ds_write_b64 v18, v[16:17]
	v_cvt_pk_bf16_f32 v12, v12, v13
	v_cvt_pk_bf16_f32 v13, v14, v15
	v_or_b32_e32 v14, s6, v96
	s_lshl_b32 s70, s5, 6
	s_lshl_b32 s5, s36, 4
	s_lshl_b32 s6, s36, 1
	v_lshlrev_b32_e32 v186, 9, v14
	v_bitop3_b32 v187, s5, v98, v202 bitop3:0x6c
	s_and_b32 s5, s36, 0xfffff0
	s_and_b32 s6, s6, 8
	v_add3_u32 v14, v2, v186, s70
	s_or_b32 s5, s6, s5
	s_lshr_b32 s6, s36, 1
	v_add3_u32 v14, v14, v136, v137
	s_lshl_b32 s71, s36, 8
	s_and_b32 s6, s6, 4
	ds_write_b64 v14, v[12:13] offset:32768
	v_cvt_pk_bf16_f32 v8, v8, v9
	v_cvt_pk_bf16_f32 v9, v10, v11
	v_add_u32_e32 v10, s71, v97
	s_or_b32 s4, s6, s4
	v_add3_u32 v10, v10, v187, v138
	s_lshr_b32 s5, s5, 1
; __device__ __forceinline__ void attn_sample_unit(int b, int h, int split, const bf16* __restrict__ Q, const float* __restrict__ cache_k, const float* __restrict__ cache_v, ...
;     ...
;     SL_LOAD(0); SL_WRITE(0); SL_LOAD(1);
;     __syncthreads();
;     for (int j = 0; j < nT; ++j) {
;       if (j + 1 < nT) { SL_WRITE((j + 1) & 1); if (j + 2 < nT) SL_LOAD(j + 2); }
	s_lshl_b32 s4, s4, 6
	ds_write_b64 v10, v[8:9]
	v_cvt_pk_bf16_f32 v4, v4, v5
	v_cvt_pk_bf16_f32 v5, v6, v7
	v_or_b32_e32 v6, s5, v96
	s_add_u32 s5, s18, 0x80000
	s_addc_u32 s8, s19, 0
	s_add_u32 s6, s44, s5
	s_addc_u32 s7, s45, s8
	s_add_u32 s6, s6, s40
	s_addc_u32 s7, s7, 0
	s_add_u32 s5, s46, s5
	v_lshlrev_b32_e32 v188, 9, v6
	s_addc_u32 s9, s47, s8
	v_add3_u32 v2, v2, v188, s4
	s_add_u32 s8, s5, s40
	v_add3_u32 v2, v2, v136, v137
	s_addc_u32 s9, s9, 0
	ds_write_b64 v2, v[4:5] offset:32768
	v_lshl_add_u64 v[4:5], s[6:7], 0, v[100:101]
	v_lshl_add_u64 v[6:7], s[8:9], 0, v[100:101]
	v_lshl_add_u64 v[4:5], v[4:5], 0, s[72:73]
	v_lshl_add_u64 v[6:7], v[6:7], 0, s[72:73]
	global_load_dwordx4 v[128:131], v100, s[6:7] nt
	global_load_dwordx4 v[124:127], v100, s[8:9] nt
	global_load_dwordx4 v[120:123], v[4:5], off nt
	global_load_dwordx4 v[116:119], v[6:7], off nt
	v_lshl_add_u64 v[4:5], v[4:5], 0, s[72:73]
	v_lshl_add_u64 v[6:7], v[6:7], 0, s[72:73]
	global_load_dwordx4 v[112:115], v[4:5], off nt
	global_load_dwordx4 v[108:111], v[6:7], off nt
	v_lshl_add_u64 v[4:5], v[4:5], 0, s[72:73]
	v_lshl_add_u64 v[6:7], v[6:7], 0, s[72:73]
	global_load_dwordx4 v[104:107], v[4:5], off nt
	global_load_dwordx4 v[100:103], v[6:7], off nt
	v_lshl_add_u64 v[4:5], v[4:5], 0, s[72:73]
	v_lshl_add_u64 v[6:7], v[6:7], 0, s[72:73]
	global_load_dwordx4 v[96:99], v[4:5], off nt
	global_load_dwordx4 v[88:91], v[6:7], off nt
	v_lshl_add_u64 v[4:5], v[4:5], 0, s[72:73]
	v_lshl_add_u64 v[6:7], v[6:7], 0, s[72:73]
	global_load_dwordx4 v[92:95], v[4:5], off nt
	global_load_dwordx4 v[80:83], v[6:7], off nt
	v_lshl_add_u64 v[4:5], v[4:5], 0, s[72:73]
	v_lshl_add_u64 v[6:7], v[6:7], 0, s[72:73]
	global_load_dwordx4 v[84:87], v[4:5], off nt
	global_load_dwordx4 v[72:75], v[6:7], off nt
	v_lshl_add_u64 v[4:5], v[4:5], 0, s[72:73]
	v_lshl_add_u64 v[6:7], v[6:7], 0, s[72:73]
	global_load_dwordx4 v[76:79], v[4:5], off nt
	global_load_dwordx4 v[64:67], v[6:7], off nt
	v_lshl_add_u64 v[4:5], v[4:5], 0, s[72:73]
	v_lshl_add_u64 v[6:7], v[6:7], 0, s[72:73]
	global_load_dwordx4 v[68:71], v[4:5], off nt
	global_load_dwordx4 v[56:59], v[6:7], off nt
	v_lshl_add_u64 v[4:5], v[4:5], 0, s[72:73]
	v_lshl_add_u64 v[6:7], v[6:7], 0, s[72:73]
	global_load_dwordx4 v[60:63], v[4:5], off nt
	global_load_dwordx4 v[48:51], v[6:7], off nt
	v_lshl_add_u64 v[4:5], v[4:5], 0, s[72:73]
	v_lshl_add_u64 v[6:7], v[6:7], 0, s[72:73]
	global_load_dwordx4 v[52:55], v[4:5], off nt
	global_load_dwordx4 v[40:43], v[6:7], off nt
	v_lshl_add_u64 v[4:5], v[4:5], 0, s[72:73]
	v_lshl_add_u64 v[6:7], v[6:7], 0, s[72:73]
	global_load_dwordx4 v[44:47], v[4:5], off nt
	global_load_dwordx4 v[32:35], v[6:7], off nt
	v_lshl_add_u64 v[4:5], v[4:5], 0, s[72:73]
	v_lshl_add_u64 v[6:7], v[6:7], 0, s[72:73]
	global_load_dwordx4 v[36:39], v[4:5], off nt
	global_load_dwordx4 v[24:27], v[6:7], off nt
	v_lshl_add_u64 v[4:5], v[4:5], 0, s[72:73]
	v_lshl_add_u64 v[6:7], v[6:7], 0, s[72:73]
	global_load_dwordx4 v[28:31], v[4:5], off nt
	global_load_dwordx4 v[16:19], v[6:7], off nt
	v_lshl_add_u64 v[4:5], v[4:5], 0, s[72:73]
	v_lshl_add_u64 v[6:7], v[6:7], 0, s[72:73]
	global_load_dwordx4 v[20:23], v[4:5], off nt
	global_load_dwordx4 v[8:11], v[6:7], off nt
	v_lshl_add_u64 v[134:135], v[4:5], 0, s[72:73]
	v_lshl_add_u64 v[156:157], v[6:7], 0, s[72:73]
	global_load_dwordx4 v[12:15], v[134:135], off nt
	global_load_dwordx4 v[4:7], v[156:157], off nt
	s_lshl_b64 s[6:7], s[20:21], 17
	s_add_u32 s5, s56, s6
	s_addc_u32 s14, s57, s7
	s_lshl_b64 s[8:9], s[10:11], 13
	s_add_u32 s5, s5, s8
	s_addc_u32 s10, s14, s9
	s_add_u32 s6, s52, s6
	s_addc_u32 s7, s53, s7
	s_add_u32 s6, s6, s8
	s_addc_u32 s7, s7, s9
	s_lshl_b64 s[14:15], s[20:21], 25
	s_or_b32 s14, s14, s38
	s_add_u32 s14, s14, s8
	s_addc_u32 s15, s15, s9
	s_add_u32 s8, s58, s14
	s_addc_u32 s9, s59, s15
	v_lshlrev_b32_e32 v2, 2, v132
	s_add_u32 s14, s62, s14
	s_mov_b32 s30, s76
	v_lshl_add_u64 v[132:133], v[134:135], 0, s[72:73]
	v_lshl_add_u64 v[134:135], v[156:157], 0, s[72:73]
	s_addc_u32 s15, s63, s15
	s_mov_b64 s[20:21], 0
	s_mov_b32 s76, 0x10000
	v_lshlrev_b32_e32 v2, 2, v2
	s_waitcnt lgkmcnt(0)
	s_barrier
	s_branch .LBB0_372

; __device__ __forceinline__ void attn_sample_unit(int b, int h, int split, const bf16* __restrict__ Q, const float* __restrict__ cache_k, const float* __restrict__ cache_v, ...
;     ...
;     for (int j = 0; j < nT; ++j) {
;       if (j + 1 < nT) { SL_WRITE((j + 1) & 1); if (j + 2 < nT) SL_LOAD(j + 2); }
;       __syncthreads();
.LBB0_372:
	s_and_b32 s28, s76, 0x10000
	s_add_i32 s28, s28, 0
	v_add_u32_e32 v132, s28, v139
	v_add_u32_e32 v133, s28, v140
	s_cmp_lg_u32 s20, 0xf00000
	s_cselect_b64 s[36:37], -1, 0
	s_add_u32 s28, s14, s20
	s_addc_u32 s29, s15, s21
	s_add_u32 s33, s8, s20
	s_addc_u32 s23, s9, s21
	s_cmp_eq_u32 s20, 0xf00000
	s_cselect_b64 s[38:39], -1, 0
	s_and_b64 vcc, s[38:39], exec
	s_cselect_b32 s28, s5, s28
	s_cselect_b32 s29, s10, s29
	s_cselect_b32 s23, s7, s23
	s_cselect_b32 s33, s6, s33
	s_add_u32 s38, s28, s40
	s_addc_u32 s39, s29, 0
	s_add_u32 s28, s33, s40
	s_addc_u32 s29, s23, 0
	s_and_b64 vcc, exec, s[36:37]
	s_cbranch_vccz .Lsl_new
	v_lshl_add_u64 v[240:241], s[38:39], 0, v[2:3]
	v_lshl_add_u64 v[242:243], s[28:29], 0, v[2:3]
	s_waitcnt vmcnt(30)
	v_add_u32_e32 v246, s43, v132
	v_add3_u32 v246, v246, v141, v138
	v_cvt_pk_bf16_f32 v244, v128, v129
	v_cvt_pk_bf16_f32 v245, v130, v131
	ds_write_b64 v246, v[244:245]
	v_add3_u32 v250, v133, v142, s65
	v_add3_u32 v250, v250, v136, v137
	v_cvt_pk_bf16_f32 v248, v124, v125
	v_cvt_pk_bf16_f32 v249, v126, v127
	ds_write_b64 v250, v[248:249] offset:32768
	global_load_dwordx4 v[128:131], v[240:241], off nt
	global_load_dwordx4 v[124:127], v[242:243], off nt
	s_waitcnt vmcnt(30)
	v_add_u32_e32 v246, s66, v132
	v_add3_u32 v246, v246, v143, v138
	v_cvt_pk_bf16_f32 v244, v120, v121
	v_cvt_pk_bf16_f32 v245, v122, v123
	ds_write_b64 v246, v[244:245]
	v_add3_u32 v250, v133, v144, s41
	v_add3_u32 v250, v250, v136, v137
	v_cvt_pk_bf16_f32 v248, v116, v117
	v_cvt_pk_bf16_f32 v249, v118, v119
	ds_write_b64 v250, v[248:249] offset:32768
	v_lshl_add_u64 v[240:241], v[240:241], 0, s[72:73]
	v_lshl_add_u64 v[242:243], v[242:243], 0, s[72:73]
	global_load_dwordx4 v[120:123], v[240:241], off nt
	global_load_dwordx4 v[116:119], v[242:243], off nt
	s_waitcnt vmcnt(30)
	v_add_u32_e32 v246, s67, v132
	v_add3_u32 v246, v246, v145, v138
	v_cvt_pk_bf16_f32 v244, v112, v113
	v_cvt_pk_bf16_f32 v245, v114, v115
	ds_write_b64 v246, v[244:245]
	v_add3_u32 v250, v133, v146, s77
	v_add3_u32 v250, v250, v136, v137
	v_cvt_pk_bf16_f32 v248, v108, v109
	v_cvt_pk_bf16_f32 v249, v110, v111
	ds_write_b64 v250, v[248:249] offset:32768
	v_lshl_add_u64 v[240:241], v[240:241], 0, s[72:73]
	v_lshl_add_u64 v[242:243], v[242:243], 0, s[72:73]
	global_load_dwordx4 v[112:115], v[240:241], off nt
	global_load_dwordx4 v[108:111], v[242:243], off nt
	s_waitcnt vmcnt(30)
	v_add_u32_e32 v246, s78, v132
	v_add3_u32 v246, v246, v147, v138
	v_cvt_pk_bf16_f32 v244, v104, v105
	v_cvt_pk_bf16_f32 v245, v106, v107
	ds_write_b64 v246, v[244:245]
	v_add3_u32 v250, v133, v148, s79
	v_add3_u32 v250, v250, v136, v137
	v_cvt_pk_bf16_f32 v248, v100, v101
	v_cvt_pk_bf16_f32 v249, v102, v103
	ds_write_b64 v250, v[248:249] offset:32768
	v_lshl_add_u64 v[240:241], v[240:241], 0, s[72:73]
	v_lshl_add_u64 v[242:243], v[242:243], 0, s[72:73]
	global_load_dwordx4 v[104:107], v[240:241], off nt
	global_load_dwordx4 v[100:103], v[242:243], off nt
	s_waitcnt vmcnt(30)
	v_add_u32_e32 v246, s80, v132
	v_add3_u32 v246, v246, v149, v138
	v_cvt_pk_bf16_f32 v244, v96, v97
	v_cvt_pk_bf16_f32 v245, v98, v99
	ds_write_b64 v246, v[244:245]
	v_add3_u32 v250, v133, v150, s81
	v_add3_u32 v250, v250, v136, v137
	v_cvt_pk_bf16_f32 v248, v88, v89
	v_cvt_pk_bf16_f32 v249, v90, v91
	ds_write_b64 v250, v[248:249] offset:32768
	v_lshl_add_u64 v[240:241], v[240:241], 0, s[72:73]
	v_lshl_add_u64 v[242:243], v[242:243], 0, s[72:73]
	global_load_dwordx4 v[96:99], v[240:241], off nt
	global_load_dwordx4 v[88:91], v[242:243], off nt
	s_waitcnt vmcnt(30)
	v_add_u32_e32 v246, s82, v132
	v_add3_u32 v246, v246, v151, v138
	v_cvt_pk_bf16_f32 v244, v92, v93
	v_cvt_pk_bf16_f32 v245, v94, v95
	ds_write_b64 v246, v[244:245]
	v_add3_u32 v250, v133, v152, s41
	v_add3_u32 v250, v250, v136, v137
	v_cvt_pk_bf16_f32 v248, v80, v81
	v_cvt_pk_bf16_f32 v249, v82, v83
	ds_write_b64 v250, v[248:249] offset:32768
	v_lshl_add_u64 v[240:241], v[240:241], 0, s[72:73]
	v_lshl_add_u64 v[242:243], v[242:243], 0, s[72:73]
	global_load_dwordx4 v[92:95], v[240:241], off nt
	global_load_dwordx4 v[80:83], v[242:243], off nt
	s_waitcnt vmcnt(30)
	v_add_u32_e32 v246, s83, v132
	v_add3_u32 v246, v246, v153, v138
	v_cvt_pk_bf16_f32 v244, v84, v85
	v_cvt_pk_bf16_f32 v245, v86, v87
	ds_write_b64 v246, v[244:245]
	v_add3_u32 v250, v133, v154, s84
	v_add3_u32 v250, v250, v136, v137
	v_cvt_pk_bf16_f32 v248, v72, v73
	v_cvt_pk_bf16_f32 v249, v74, v75
	ds_write_b64 v250, v[248:249] offset:32768
	v_lshl_add_u64 v[240:241], v[240:241], 0, s[72:73]
	v_lshl_add_u64 v[242:243], v[242:243], 0, s[72:73]
	global_load_dwordx4 v[84:87], v[240:241], off nt
	global_load_dwordx4 v[72:75], v[242:243], off nt
	s_waitcnt vmcnt(30)
	v_add_u32_e32 v246, s85, v132
	v_add3_u32 v246, v246, v155, v138
	v_cvt_pk_bf16_f32 v244, v76, v77
	v_cvt_pk_bf16_f32 v245, v78, v79
	ds_write_b64 v246, v[244:245]
	v_add3_u32 v250, v133, v172, s86
	v_add3_u32 v250, v250, v136, v137
	v_cvt_pk_bf16_f32 v248, v64, v65
	v_cvt_pk_bf16_f32 v249, v66, v67
	ds_write_b64 v250, v[248:249] offset:32768
	v_lshl_add_u64 v[240:241], v[240:241], 0, s[72:73]
	v_lshl_add_u64 v[242:243], v[242:243], 0, s[72:73]
	global_load_dwordx4 v[76:79], v[240:241], off nt
	global_load_dwordx4 v[64:67], v[242:243], off nt
	s_waitcnt vmcnt(30)
	v_add_u32_e32 v246, s87, v132
	v_add3_u32 v246, v246, v173, v138
	v_cvt_pk_bf16_f32 v244, v68, v69
	v_cvt_pk_bf16_f32 v245, v70, v71
	ds_write_b64 v246, v[244:245]
	v_add3_u32 v250, v133, v174, s88
	v_add3_u32 v250, v250, v136, v137
	v_cvt_pk_bf16_f32 v248, v56, v57
	v_cvt_pk_bf16_f32 v249, v58, v59
	ds_write_b64 v250, v[248:249] offset:32768
	v_lshl_add_u64 v[240:241], v[240:241], 0, s[72:73]
	v_lshl_add_u64 v[242:243], v[242:243], 0, s[72:73]
	global_load_dwordx4 v[68:71], v[240:241], off nt
	global_load_dwordx4 v[56:59], v[242:243], off nt
	s_waitcnt vmcnt(30)
; __device__ __forceinline__ void attn_sample_unit(int b, int h, int split, const bf16* __restrict__ Q, const float* __restrict__ cache_k, const float* __restrict__ cache_v, ...
;     ...
;     for (int j = 0; j < nT; ++j) {
;       if (j + 1 < nT) { SL_WRITE((j + 1) & 1); if (j + 2 < nT) SL_LOAD(j + 2); }
;       __syncthreads();
	v_add_u32_e32 v246, s89, v132
	v_add3_u32 v246, v246, v175, v138
	v_cvt_pk_bf16_f32 v244, v60, v61
	v_cvt_pk_bf16_f32 v245, v62, v63
	ds_write_b64 v246, v[244:245]
	v_add3_u32 v250, v133, v176, s41
	v_add3_u32 v250, v250, v136, v137
	v_cvt_pk_bf16_f32 v248, v48, v49
	v_cvt_pk_bf16_f32 v249, v50, v51
	ds_write_b64 v250, v[248:249] offset:32768
	v_lshl_add_u64 v[240:241], v[240:241], 0, s[72:73]
	v_lshl_add_u64 v[242:243], v[242:243], 0, s[72:73]
	global_load_dwordx4 v[60:63], v[240:241], off nt
	global_load_dwordx4 v[48:51], v[242:243], off nt
	s_waitcnt vmcnt(30)
	v_add_u32_e32 v246, s90, v132
	v_add3_u32 v246, v246, v177, v138
	v_cvt_pk_bf16_f32 v244, v52, v53
	v_cvt_pk_bf16_f32 v245, v54, v55
	ds_write_b64 v246, v[244:245]
	v_add3_u32 v250, v133, v178, s91
	v_add3_u32 v250, v250, v136, v137
	v_cvt_pk_bf16_f32 v248, v40, v41
	v_cvt_pk_bf16_f32 v249, v42, v43
	ds_write_b64 v250, v[248:249] offset:32768
	v_lshl_add_u64 v[240:241], v[240:241], 0, s[72:73]
	v_lshl_add_u64 v[242:243], v[242:243], 0, s[72:73]
	global_load_dwordx4 v[52:55], v[240:241], off nt
	global_load_dwordx4 v[40:43], v[242:243], off nt
	s_waitcnt vmcnt(30)
	v_add_u32_e32 v246, s92, v132
	v_add3_u32 v246, v246, v179, v138
	v_cvt_pk_bf16_f32 v244, v44, v45
	v_cvt_pk_bf16_f32 v245, v46, v47
	ds_write_b64 v246, v[244:245]
	v_add3_u32 v250, v133, v180, s93
	v_add3_u32 v250, v250, v136, v137
	v_cvt_pk_bf16_f32 v248, v32, v33
	v_cvt_pk_bf16_f32 v249, v34, v35
	ds_write_b64 v250, v[248:249] offset:32768
	v_lshl_add_u64 v[240:241], v[240:241], 0, s[72:73]
	v_lshl_add_u64 v[242:243], v[242:243], 0, s[72:73]
	global_load_dwordx4 v[44:47], v[240:241], off nt
	global_load_dwordx4 v[32:35], v[242:243], off nt
	s_waitcnt vmcnt(30)
	v_add_u32_e32 v246, s94, v132
	v_add3_u32 v246, v246, v181, v138
	v_cvt_pk_bf16_f32 v244, v36, v37
	v_cvt_pk_bf16_f32 v245, v38, v39
	ds_write_b64 v246, v[244:245]
	v_add3_u32 v250, v133, v182, s95
	v_add3_u32 v250, v250, v136, v137
	v_cvt_pk_bf16_f32 v248, v24, v25
	v_cvt_pk_bf16_f32 v249, v26, v27
	ds_write_b64 v250, v[248:249] offset:32768
	v_lshl_add_u64 v[240:241], v[240:241], 0, s[72:73]
	v_lshl_add_u64 v[242:243], v[242:243], 0, s[72:73]
	global_load_dwordx4 v[36:39], v[240:241], off nt
	global_load_dwordx4 v[24:27], v[242:243], off nt
	s_waitcnt vmcnt(30)
	v_add_u32_e32 v246, s96, v132
	v_add3_u32 v246, v246, v183, v138
	v_cvt_pk_bf16_f32 v244, v28, v29
	v_cvt_pk_bf16_f32 v245, v30, v31
	ds_write_b64 v246, v[244:245]
	v_add3_u32 v250, v133, v184, s41
	v_add3_u32 v250, v250, v136, v137
	v_cvt_pk_bf16_f32 v248, v16, v17
	v_cvt_pk_bf16_f32 v249, v18, v19
	ds_write_b64 v250, v[248:249] offset:32768
	v_lshl_add_u64 v[240:241], v[240:241], 0, s[72:73]
	v_lshl_add_u64 v[242:243], v[242:243], 0, s[72:73]
	global_load_dwordx4 v[28:31], v[240:241], off nt
	global_load_dwordx4 v[16:19], v[242:243], off nt
	s_waitcnt vmcnt(30)
	v_add_u32_e32 v246, s97, v132
	v_add3_u32 v246, v246, v185, v138
	v_cvt_pk_bf16_f32 v244, v20, v21
	v_cvt_pk_bf16_f32 v245, v22, v23
	ds_write_b64 v246, v[244:245]
	v_add3_u32 v250, v133, v186, s70
	v_add3_u32 v250, v250, v136, v137
	v_cvt_pk_bf16_f32 v248, v8, v9
	v_cvt_pk_bf16_f32 v249, v10, v11
	ds_write_b64 v250, v[248:249] offset:32768
	v_lshl_add_u64 v[240:241], v[240:241], 0, s[72:73]
	v_lshl_add_u64 v[242:243], v[242:243], 0, s[72:73]
	global_load_dwordx4 v[20:23], v[240:241], off nt
	global_load_dwordx4 v[8:11], v[242:243], off nt
	s_waitcnt vmcnt(30)
	v_add_u32_e32 v246, s71, v132
	v_add3_u32 v246, v246, v187, v138
	v_cvt_pk_bf16_f32 v244, v12, v13
	v_cvt_pk_bf16_f32 v245, v14, v15
	ds_write_b64 v246, v[244:245]
	v_add3_u32 v250, v133, v188, s4
	v_add3_u32 v250, v250, v136, v137
	v_cvt_pk_bf16_f32 v248, v4, v5
	v_cvt_pk_bf16_f32 v249, v6, v7
	ds_write_b64 v250, v[248:249] offset:32768
	v_lshl_add_u64 v[240:241], v[240:241], 0, s[72:73]
	v_lshl_add_u64 v[242:243], v[242:243], 0, s[72:73]
	global_load_dwordx4 v[12:15], v[240:241], off nt
	global_load_dwordx4 v[4:7], v[242:243], off nt
	s_branch .LBB0_371
.Lsl_new:
	v_lshl_add_u64 v[240:241], s[38:39], 0, v[2:3]
	v_lshl_add_u64 v[242:243], s[28:29], 0, v[2:3]
	s_waitcnt vmcnt(30)
	v_add_u32_e32 v246, s43, v132
	v_add3_u32 v246, v246, v141, v138
	v_cvt_pk_bf16_f32 v244, v128, v129
	v_cvt_pk_bf16_f32 v245, v130, v131
	ds_write_b64 v246, v[244:245]
	v_add3_u32 v250, v133, v142, s65
	v_add3_u32 v250, v250, v136, v137
	v_cvt_pk_bf16_f32 v248, v124, v125
	v_cvt_pk_bf16_f32 v249, v126, v127
	ds_write_b64 v250, v[248:249] offset:32768
	global_load_dwordx4 v[128:131], v[240:241], off nt
	global_load_dwordx4 v[124:127], v[242:243], off nt
	s_waitcnt vmcnt(30)
	v_add_u32_e32 v246, s66, v132
	v_add3_u32 v246, v246, v143, v138
	v_cvt_pk_bf16_f32 v244, v120, v121
	v_cvt_pk_bf16_f32 v245, v122, v123
	ds_write_b64 v246, v[244:245]
	v_add3_u32 v250, v133, v144, s41
	v_add3_u32 v250, v250, v136, v137
	v_cvt_pk_bf16_f32 v248, v116, v117
	v_cvt_pk_bf16_f32 v249, v118, v119
	ds_write_b64 v250, v[248:249] offset:32768
	v_lshl_add_u64 v[240:241], v[240:241], 0, s[72:73]
	v_lshl_add_u64 v[242:243], v[242:243], 0, s[72:73]
	global_load_dwordx4 v[120:123], v[240:241], off nt
	global_load_dwordx4 v[116:119], v[242:243], off nt
	s_waitcnt vmcnt(30)
	v_add_u32_e32 v246, s67, v132
	v_add3_u32 v246, v246, v145, v138
	v_cvt_pk_bf16_f32 v244, v112, v113
	v_cvt_pk_bf16_f32 v245, v114, v115
	ds_write_b64 v246, v[244:245]
	v_add3_u32 v250, v133, v146, s77
	v_add3_u32 v250, v250, v136, v137
	v_cvt_pk_bf16_f32 v248, v108, v109
	v_cvt_pk_bf16_f32 v249, v110, v111
	ds_write_b64 v250, v[248:249] offset:32768
	v_lshl_add_u64 v[240:241], v[240:241], 0, s[72:73]
	v_lshl_add_u64 v[242:243], v[242:243], 0, s[72:73]
	global_load_dwordx4 v[112:115], v[240:241], off nt
	global_load_dwordx4 v[108:111], v[242:243], off nt
	s_waitcnt vmcnt(30)
	v_add_u32_e32 v246, s78, v132
	v_add3_u32 v246, v246, v147, v138
	v_cvt_pk_bf16_f32 v244, v104, v105
	v_cvt_pk_bf16_f32 v245, v106, v107
	ds_write_b64 v246, v[244:245]
	v_add3_u32 v250, v133, v148, s79
	v_add3_u32 v250, v250, v136, v137
	v_cvt_pk_bf16_f32 v248, v100, v101
	v_cvt_pk_bf16_f32 v249, v102, v103
	ds_write_b64 v250, v[248:249] offset:32768
	v_lshl_add_u64 v[240:241], v[240:241], 0, s[72:73]
	v_lshl_add_u64 v[242:243], v[242:243], 0, s[72:73]
	global_load_dwordx4 v[104:107], v[240:241], off nt
	global_load_dwordx4 v[100:103], v[242:243], off nt
	s_waitcnt vmcnt(30)
	v_add_u32_e32 v246, s80, v132
	v_add3_u32 v246, v246, v149, v138
	v_cvt_pk_bf16_f32 v244, v96, v97
	v_cvt_pk_bf16_f32 v245, v98, v99
	ds_write_b64 v246, v[244:245]
	v_add3_u32 v250, v133, v150, s81
	v_add3_u32 v250, v250, v136, v137
	v_cvt_pk_bf16_f32 v248, v88, v89
	v_cvt_pk_bf16_f32 v249, v90, v91
	ds_write_b64 v250, v[248:249] offset:32768
	v_mov_b32_e32 v96, v3
	v_mov_b32_e32 v97, v3
	v_mov_b32_e32 v98, v3
	v_mov_b32_e32 v99, v3
	v_mov_b32_e32 v88, v3
	v_mov_b32_e32 v89, v3
	v_mov_b32_e32 v90, v3
	v_mov_b32_e32 v91, v3
	s_waitcnt vmcnt(28)
	v_add_u32_e32 v246, s82, v132
	v_add3_u32 v246, v246, v151, v138
	v_cvt_pk_bf16_f32 v244, v92, v93
	v_cvt_pk_bf16_f32 v245, v94, v95
	ds_write_b64 v246, v[244:245]
	v_add3_u32 v250, v133, v152, s41
	v_add3_u32 v250, v250, v136, v137
	v_cvt_pk_bf16_f32 v248, v80, v81
	v_cvt_pk_bf16_f32 v249, v82, v83
	ds_write_b64 v250, v[248:249] offset:32768
	v_mov_b32_e32 v92, v3
	v_mov_b32_e32 v93, v3
	v_mov_b32_e32 v94, v3
	v_mov_b32_e32 v95, v3
	v_mov_b32_e32 v80, v3
	v_mov_b32_e32 v81, v3
	v_mov_b32_e32 v82, v3
	v_mov_b32_e32 v83, v3
	s_waitcnt vmcnt(26)
	v_add_u32_e32 v246, s83, v132
	v_add3_u32 v246, v246, v153, v138
	v_cvt_pk_bf16_f32 v244, v84, v85
	v_cvt_pk_bf16_f32 v245, v86, v87
	ds_write_b64 v246, v[244:245]
	v_add3_u32 v250, v133, v154, s84
	v_add3_u32 v250, v250, v136, v137
	v_cvt_pk_bf16_f32 v248, v72, v73
	v_cvt_pk_bf16_f32 v249, v74, v75
	ds_write_b64 v250, v[248:249] offset:32768
	v_mov_b32_e32 v84, v3
	v_mov_b32_e32 v85, v3
	v_mov_b32_e32 v86, v3
	v_mov_b32_e32 v87, v3
	v_mov_b32_e32 v72, v3
	v_mov_b32_e32 v73, v3
	v_mov_b32_e32 v74, v3
	v_mov_b32_e32 v75, v3
	s_waitcnt vmcnt(24)
	v_add_u32_e32 v246, s85, v132
	v_add3_u32 v246, v246, v155, v138
	v_cvt_pk_bf16_f32 v244, v76, v77
	v_cvt_pk_bf16_f32 v245, v78, v79
	ds_write_b64 v246, v[244:245]
	v_add3_u32 v250, v133, v172, s86
	v_add3_u32 v250, v250, v136, v137
	v_cvt_pk_bf16_f32 v248, v64, v65
	v_cvt_pk_bf16_f32 v249, v66, v67
	ds_write_b64 v250, v[248:249] offset:32768
	v_mov_b32_e32 v76, v3
	v_mov_b32_e32 v77, v3
	v_mov_b32_e32 v78, v3
	v_mov_b32_e32 v79, v3
	v_mov_b32_e32 v64, v3
	v_mov_b32_e32 v65, v3
	v_mov_b32_e32 v66, v3
	v_mov_b32_e32 v67, v3
	s_waitcnt vmcnt(22)
	v_add_u32_e32 v246, s87, v132
	v_add3_u32 v246, v246, v173, v138
	v_cvt_pk_bf16_f32 v244, v68, v69
	v_cvt_pk_bf16_f32 v245, v70, v71
	ds_write_b64 v246, v[244:245]
	v_add3_u32 v250, v133, v174, s88
	v_add3_u32 v250, v250, v136, v137
	v_cvt_pk_bf16_f32 v248, v56, v57
	v_cvt_pk_bf16_f32 v249, v58, v59
	ds_write_b64 v250, v[248:249] offset:32768
	v_mov_b32_e32 v68, v3
	v_mov_b32_e32 v69, v3
	v_mov_b32_e32 v70, v3
	v_mov_b32_e32 v71, v3
	v_mov_b32_e32 v56, v3
	v_mov_b32_e32 v57, v3
	v_mov_b32_e32 v58, v3
	v_mov_b32_e32 v59, v3
	s_waitcnt vmcnt(20)
	v_add_u32_e32 v246, s89, v132
	v_add3_u32 v246, v246, v175, v138
	v_cvt_pk_bf16_f32 v244, v60, v61
	v_cvt_pk_bf16_f32 v245, v62, v63
	ds_write_b64 v246, v[244:245]
	v_add3_u32 v250, v133, v176, s41
	v_add3_u32 v250, v250, v136, v137
	v_cvt_pk_bf16_f32 v248, v48, v49
	v_cvt_pk_bf16_f32 v249, v50, v51
	ds_write_b64 v250, v[248:249] offset:32768
	v_mov_b32_e32 v60, v3
	v_mov_b32_e32 v61, v3
	v_mov_b32_e32 v62, v3
	v_mov_b32_e32 v63, v3
	v_mov_b32_e32 v48, v3
	v_mov_b32_e32 v49, v3
	v_mov_b32_e32 v50, v3
	v_mov_b32_e32 v51, v3
	s_waitcnt vmcnt(18)
	v_add_u32_e32 v246, s90, v132
	v_add3_u32 v246, v246, v177, v138
	v_cvt_pk_bf16_f32 v244, v52, v53
	v_cvt_pk_bf16_f32 v245, v54, v55
	ds_write_b64 v246, v[244:245]
	v_add3_u32 v250, v133, v178, s91
	v_add3_u32 v250, v250, v136, v137
	v_cvt_pk_bf16_f32 v248, v40, v41
	v_cvt_pk_bf16_f32 v249, v42, v43
	ds_write_b64 v250, v[248:249] offset:32768
	v_mov_b32_e32 v52, v3
	v_mov_b32_e32 v53, v3
	v_mov_b32_e32 v54, v3
	v_mov_b32_e32 v55, v3
	v_mov_b32_e32 v40, v3
	v_mov_b32_e32 v41, v3
	v_mov_b32_e32 v42, v3
	v_mov_b32_e32 v43, v3
	s_waitcnt vmcnt(16)
	v_add_u32_e32 v246, s92, v132
	v_add3_u32 v246, v246, v179, v138
	v_cvt_pk_bf16_f32 v244, v44, v45
	v_cvt_pk_bf16_f32 v245, v46, v47
	ds_write_b64 v246, v[244:245]
	v_add3_u32 v250, v133, v180, s93
	v_add3_u32 v250, v250, v136, v137
	v_cvt_pk_bf16_f32 v248, v32, v33
	v_cvt_pk_bf16_f32 v249, v34, v35
	ds_write_b64 v250, v[248:249] offset:32768
	v_mov_b32_e32 v44, v3
	v_mov_b32_e32 v45, v3
	v_mov_b32_e32 v46, v3
	v_mov_b32_e32 v47, v3
	v_mov_b32_e32 v32, v3
	v_mov_b32_e32 v33, v3
	v_mov_b32_e32 v34, v3
	v_mov_b32_e32 v35, v3
	s_waitcnt vmcnt(14)
	v_add_u32_e32 v246, s94, v132
	v_add3_u32 v246, v246, v181, v138
	v_cvt_pk_bf16_f32 v244, v36, v37
	v_cvt_pk_bf16_f32 v245, v38, v39
	ds_write_b64 v246, v[244:245]
	v_add3_u32 v250, v133, v182, s95
	v_add3_u32 v250, v250, v136, v137
	v_cvt_pk_bf16_f32 v248, v24, v25
	v_cvt_pk_bf16_f32 v249, v26, v27
	ds_write_b64 v250, v[248:249] offset:32768
	v_mov_b32_e32 v36, v3
	v_mov_b32_e32 v37, v3
	v_mov_b32_e32 v38, v3
	v_mov_b32_e32 v39, v3
	v_mov_b32_e32 v24, v3
	v_mov_b32_e32 v25, v3
	v_mov_b32_e32 v26, v3
	v_mov_b32_e32 v27, v3
	s_waitcnt vmcnt(12)
	v_add_u32_e32 v246, s96, v132
	v_add3_u32 v246, v246, v183, v138
	v_cvt_pk_bf16_f32 v244, v28, v29
	v_cvt_pk_bf16_f32 v245, v30, v31
	ds_write_b64 v246, v[244:245]
	v_add3_u32 v250, v133, v184, s41
	v_add3_u32 v250, v250, v136, v137
	v_cvt_pk_bf16_f32 v248, v16, v17
	v_cvt_pk_bf16_f32 v249, v18, v19
	ds_write_b64 v250, v[248:249] offset:32768
	v_mov_b32_e32 v28, v3
	v_mov_b32_e32 v29, v3
	v_mov_b32_e32 v30, v3
	v_mov_b32_e32 v31, v3
	v_mov_b32_e32 v16, v3
	v_mov_b32_e32 v17, v3
	v_mov_b32_e32 v18, v3
	v_mov_b32_e32 v19, v3
	s_waitcnt vmcnt(10)
	v_add_u32_e32 v246, s97, v132
	v_add3_u32 v246, v246, v185, v138
	v_cvt_pk_bf16_f32 v244, v20, v21
	v_cvt_pk_bf16_f32 v245, v22, v23
	ds_write_b64 v246, v[244:245]
	v_add3_u32 v250, v133, v186, s70
	v_add3_u32 v250, v250, v136, v137
	v_cvt_pk_bf16_f32 v248, v8, v9
	v_cvt_pk_bf16_f32 v249, v10, v11
	ds_write_b64 v250, v[248:249] offset:32768
	v_mov_b32_e32 v20, v3
	v_mov_b32_e32 v21, v3
	v_mov_b32_e32 v22, v3
	v_mov_b32_e32 v23, v3
	v_mov_b32_e32 v8, v3
	v_mov_b32_e32 v9, v3
	v_mov_b32_e32 v10, v3
	v_mov_b32_e32 v11, v3
	s_waitcnt vmcnt(8)
	v_add_u32_e32 v246, s71, v132
	v_add3_u32 v246, v246, v187, v138
	v_cvt_pk_bf16_f32 v244, v12, v13
	v_cvt_pk_bf16_f32 v245, v14, v15
	ds_write_b64 v246, v[244:245]
	v_add3_u32 v250, v133, v188, s4
	v_add3_u32 v250, v250, v136, v137
	v_cvt_pk_bf16_f32 v248, v4, v5
	v_cvt_pk_bf16_f32 v249, v6, v7
	ds_write_b64 v250, v[248:249] offset:32768
	v_mov_b32_e32 v12, v3
	v_mov_b32_e32 v13, v3
	v_mov_b32_e32 v14, v3
	v_mov_b32_e32 v15, v3
	v_mov_b32_e32 v4, v3
	v_mov_b32_e32 v5, v3
	v_mov_b32_e32 v6, v3
	v_mov_b32_e32 v7, v3
	s_branch .LBB0_371
